# P64: out-projection epilogue - the wait after issuing the next row group's two residual loads no longer waits for them (vmcnt(2)); their first use is already covered by later counted waits
# baseline (speedup 1.0000x reference)
.LBB0_1115:
	s_waitcnt vmcnt(0)
	s_andn2_b64 vcc, exec, s[30:31]
	s_cbranch_vccnz .LBB0_1117

.LBB0_1117:
	s_waitcnt vmcnt(2)
	v_pk_add_f32 v[200:201], v[200:201], 1.0 op_sel_hi:[1,0]
	v_pk_add_f32 v[198:199], v[198:199], 1.0 op_sel_hi:[1,0]
	v_pk_add_f32 v[166:167], v[166:167], 1.0 op_sel_hi:[1,0]
	v_pk_add_f32 v[168:169], v[168:169], 1.0 op_sel_hi:[1,0]
	v_pk_mul_f32 v[196:197], v[196:197], v[200:201]
	v_pk_mul_f32 v[194:195], v[194:195], v[198:199]
	v_pk_mul_f32 v[198:199], v[164:165], v[168:169]
	v_pk_mul_f32 v[200:201], v[162:163], v[166:167]
	global_load_dwordx4 v[166:169], v[202:203], off
	global_load_dwordx4 v[162:165], v[204:205], off
	v_pk_add_f32 v[192:193], v[192:193], 1.0 op_sel_hi:[1,0]
	v_pk_add_f32 v[182:183], v[182:183], 1.0 op_sel_hi:[1,0]
	v_pk_add_f32 v[190:191], v[190:191], 1.0 op_sel_hi:[1,0]
	v_pk_mul_f32 v[188:189], v[188:189], v[192:193]
	v_pk_mul_f32 v[178:179], v[178:179], v[182:183]
	v_lshl_add_u64 v[182:183], v[226:227], 1, s[46:47]
	v_pk_fma_f32 v[160:161], v[160:161], v[64:65], v[242:243]
	v_pk_fma_f32 v[158:159], v[158:159], v[62:63], v[240:241]
	v_pk_fma_f32 v[192:193], v[154:155], v[58:59], v[236:237]
	v_cvt_pk_bf16_f32 v154, v158, v159
	v_cvt_pk_bf16_f32 v155, v160, v161
	v_pk_mul_f32 v[186:187], v[186:187], v[190:191]
	v_pk_fma_f32 v[190:191], v[156:157], v[60:61], v[238:239]
	v_cvt_pk_bf16_f32 v156, v192, v193
	v_pk_add_f32 v[184:185], v[184:185], 1.0 op_sel_hi:[1,0]
	v_cvt_pk_bf16_f32 v157, v190, v191
	global_store_dwordx4 v[182:183], v[154:157], off
	v_ashrrev_i32_e32 v223, 31, v222
	v_pk_mul_f32 v[180:181], v[180:181], v[184:185]
	v_mul_f32_e32 v154, v158, v158
	v_mul_f32_e32 v155, v160, v160
	v_fmac_f32_e32 v154, v159, v159
	v_fmac_f32_e32 v155, v161, v161
	v_add_f32_e32 v154, v155, v154
	v_mul_f32_e32 v155, v192, v192
	v_fmac_f32_e32 v155, v193, v193
	v_add_f32_e32 v154, v155, v154
	v_mul_f32_e32 v155, v190, v190
	v_fmac_f32_e32 v155, v191, v191
	v_lshlrev_b64 v[184:185], 11, v[222:223]
	v_add_f32_e32 v202, v155, v154
	v_pk_mul_f32 v[156:157], v[196:197], v[160:161]
	v_pk_mul_f32 v[154:155], v[194:195], v[158:159]
	v_pk_mul_f32 v[158:159], v[198:199], v[190:191]
	v_pk_mul_f32 v[160:161], v[200:201], v[192:193]
	v_cvt_pk_bf16_f32 v154, v154, v155
	v_cvt_pk_bf16_f32 v155, v156, v157
	v_pk_fma_f32 v[152:153], v[152:153], v[56:57], v[234:235]
	v_cvt_pk_bf16_f32 v156, v160, v161
	v_cvt_pk_bf16_f32 v157, v158, v159
	v_lshl_add_u64 v[158:159], s[10:11], 0, v[184:185]
	v_lshl_add_u64 v[158:159], v[220:221], 1, v[158:159]
	global_store_dwordx4 v[158:159], v[154:157], off
	v_pk_fma_f32 v[150:151], v[150:151], v[54:55], v[232:233]
	s_lshl_b32 s28, s28, 2
	v_pk_fma_f32 v[156:157], v[146:147], v[50:51], v[228:229]
	v_cvt_pk_bf16_f32 v146, v150, v151
	v_cvt_pk_bf16_f32 v147, v152, v153
	v_pk_fma_f32 v[154:155], v[148:149], v[52:53], v[230:231]
	v_cvt_pk_bf16_f32 v148, v156, v157
	s_ashr_i32 s29, s28, 31
	v_cvt_pk_bf16_f32 v149, v154, v155
	global_store_dwordx4 v[182:183], v[146:149], off offset:256
	s_nop 1
	v_mul_f32_e32 v146, v150, v150
	v_mul_f32_e32 v147, v152, v152
	v_fmac_f32_e32 v146, v151, v151
	v_fmac_f32_e32 v147, v153, v153
	v_add_f32_e32 v146, v147, v146
	v_mul_f32_e32 v147, v157, v157
	v_fmac_f32_e32 v147, v156, v156
	v_add_f32_e32 v146, v147, v146
	v_mul_f32_e32 v147, v154, v154
	v_fmac_f32_e32 v147, v155, v155
	v_add_f32_e32 v146, v147, v146
	v_add_f32_e32 v160, v202, v146
	v_pk_mul_f32 v[146:147], v[186:187], v[150:151]
	v_pk_mul_f32 v[150:151], v[180:181], v[154:155]
	ds_swizzle_b32 v154, v160 offset:swizzle(SWAP,16)
	v_pk_mul_f32 v[148:149], v[188:189], v[152:153]
	v_cvt_pk_bf16_f32 v146, v146, v147
	v_pk_mul_f32 v[152:153], v[178:179], v[156:157]
	v_cvt_pk_bf16_f32 v147, v148, v149
	s_nop 0
	v_cvt_pk_bf16_f32 v148, v152, v153
	v_cvt_pk_bf16_f32 v149, v150, v151
	global_store_dwordx4 v[158:159], v[146:149], off offset:256
	s_waitcnt lgkmcnt(0)
	s_nop 0
	v_add_f32_e32 v146, v160, v154
	v_mov_b32_e32 v147, v146
	s_nop 1
	v_permlane32_swap_b32_e32 v146, v147
	s_and_saveexec_b64 s[30:31], s[2:3]
	s_cbranch_execz .LBB0_1119
	v_lshlrev_b64 v[148:149], 6, v[222:223]
	v_lshl_add_u64 v[148:149], s[14:15], 0, v[148:149]
	v_lshl_add_u64 v[148:149], s[28:29], 2, v[148:149]
	s_lshl_b32 s36, s64, 2
	v_lshl_add_u64 v[148:149], v[148:149], 0, s[36:37]
	v_add_f32_e32 v146, v146, v147
	global_store_dword v[148:149], v146, off
